# v28 + non-temporal hint on the final norm phase's x/T1/T2 row loads and its output stores
# baseline (speedup 1.0000x reference)
.LBB0_1001:
	s_add_u32 s4, s64, s20
	s_mov_b32 s0, s17
	s_mov_b32 s3, s7
	s_addc_u32 s5, s65, s21
	s_and_b32 s1, s26, 0xffff
	buffer_load_dwordx4 v[0:3], v92, s[8:11], 0 offen
	buffer_load_dwordx4 v[4:7], v92, s[8:11], s19 offen
	buffer_load_dwordx4 v[8:11], v94, s[8:11], 0 offen
	buffer_load_dwordx4 v[12:15], v94, s[8:11], s19 offen
	buffer_load_dwordx4 v[16:19], v95, s[8:11], 0 offen
	buffer_load_dwordx4 v[20:23], v95, s[8:11], s19 offen
	buffer_load_dwordx4 v[24:27], v96, s[8:11], 0 offen
	buffer_load_dwordx4 v[28:31], v96, s[8:11], s19 offen
	buffer_load_dwordx2 v[176:177], v93, s[0:3], 0 offen nt
	buffer_load_dwordx2 v[178:179], v97, s[0:3], 0 offen nt
	buffer_load_dwordx2 v[180:181], v98, s[0:3], 0 offen nt
	buffer_load_dwordx2 v[182:183], v99, s[0:3], 0 offen nt
	s_and_b32 s5, s5, 0xffff
	buffer_load_dwordx2 v[184:185], v100, s[0:3], 0 offen nt
	buffer_load_dwordx2 v[186:187], v97, s[0:3], s19 offen nt
	buffer_load_dwordx2 v[188:189], v93, s[0:3], s19 offen nt
	buffer_load_dwordx2 v[190:191], v99, s[0:3], s19 offen nt
	buffer_load_dwordx2 v[192:193], v98, s[0:3], s19 offen nt
	buffer_load_dwordx2 v[194:195], v101, s[0:3], 0 offen nt
	buffer_load_dwordx2 v[196:197], v101, s[0:3], s19 offen nt
	buffer_load_dwordx2 v[198:199], v100, s[0:3], s19 offen nt
	buffer_load_dwordx2 v[200:201], v102, s[0:3], 0 offen nt
	buffer_load_dwordx2 v[202:203], v103, s[0:3], 0 offen nt
	buffer_load_dwordx2 v[204:205], v103, s[0:3], s19 offen nt
	buffer_load_dwordx2 v[206:207], v102, s[0:3], s19 offen nt
	buffer_load_dwordx4 v[112:115], v92, s[4:7], 0 offen nt
	buffer_load_dwordx4 v[116:119], v92, s[4:7], s19 offen nt
	buffer_load_dwordx4 v[120:123], v94, s[4:7], 0 offen nt
	buffer_load_dwordx4 v[124:127], v94, s[4:7], s19 offen nt
	buffer_load_dwordx4 v[128:131], v95, s[4:7], 0 offen nt
	buffer_load_dwordx4 v[132:135], v95, s[4:7], s19 offen nt
	buffer_load_dwordx4 v[136:139], v96, s[4:7], 0 offen nt
	buffer_load_dwordx4 v[140:143], v96, s[4:7], s19 offen nt
	buffer_load_dwordx4 v[144:147], v92, s[4:7], s2 offen nt
	buffer_load_dwordx4 v[148:151], v92, s[4:7], s27 offen nt
	buffer_load_dwordx4 v[152:155], v94, s[4:7], s2 offen nt
	buffer_load_dwordx4 v[156:159], v94, s[4:7], s27 offen nt
	buffer_load_dwordx4 v[160:163], v95, s[4:7], s2 offen nt
	buffer_load_dwordx4 v[164:167], v95, s[4:7], s27 offen nt
	buffer_load_dwordx4 v[168:171], v96, s[4:7], s2 offen nt
	buffer_load_dwordx4 v[172:175], v96, s[4:7], s27 offen nt
	s_add_u32 s12, s17, 0x8000000
	s_addc_u32 s0, s26, 0
	s_mov_b32 s14, s2
	s_mov_b32 s15, s7
	s_and_b32 s13, s0, 0xffff
	buffer_load_dwordx2 v[208:209], v93, s[12:15], 0 offen nt
	buffer_load_dwordx2 v[210:211], v97, s[12:15], 0 offen nt
	buffer_load_dwordx2 v[74:75], v97, s[12:15], s19 offen nt
	buffer_load_dwordx2 v[78:79], v93, s[12:15], s19 offen nt
	buffer_load_dwordx2 v[90:91], v98, s[12:15], 0 offen nt
	buffer_load_dwordx2 v[88:89], v99, s[12:15], 0 offen nt
	buffer_load_dwordx2 v[70:71], v99, s[12:15], s19 offen nt
	buffer_load_dwordx2 v[76:77], v98, s[12:15], s19 offen nt
	buffer_load_dwordx2 v[86:87], v100, s[12:15], 0 offen nt
	buffer_load_dwordx2 v[84:85], v101, s[12:15], 0 offen nt
	buffer_load_dwordx2 v[66:67], v101, s[12:15], s19 offen nt
	buffer_load_dwordx2 v[72:73], v100, s[12:15], s19 offen nt
	buffer_load_dwordx2 v[82:83], v102, s[12:15], 0 offen nt
	buffer_load_dwordx2 v[80:81], v103, s[12:15], 0 offen nt
	buffer_load_dwordx2 v[64:65], v103, s[12:15], s19 offen nt
	buffer_load_dwordx2 v[68:69], v102, s[12:15], s19 offen nt
	buffer_load_dwordx4 v[32:35], v92, s[8:11], s2 offen
	buffer_load_dwordx4 v[36:39], v92, s[8:11], s27 offen
	buffer_load_dwordx4 v[40:43], v94, s[8:11], s2 offen
	buffer_load_dwordx4 v[44:47], v94, s[8:11], s27 offen
	buffer_load_dwordx4 v[48:51], v95, s[8:11], s2 offen
	buffer_load_dwordx4 v[52:55], v95, s[8:11], s27 offen
	buffer_load_dwordx4 v[56:59], v96, s[8:11], s2 offen
	buffer_load_dwordx4 v[60:63], v96, s[8:11], s27 offen
	s_add_u32 s4, s60, s20
	s_addc_u32 s0, s61, s21
	s_and_b32 s5, s0, 0xffff
	s_add_i32 s16, s16, s18
	s_add_u32 s20, s20, s22
	s_addc_u32 s21, s21, s23
	s_add_u32 s17, s17, s24
	s_addc_u32 s26, s26, s25
	s_cmpk_lt_i32 s16, 0x4000
	s_waitcnt vmcnt(0)
	v_lshlrev_b32_e32 v220, 16, v184
	v_lshlrev_b32_e32 v230, 16, v186
	v_and_b32_e32 v231, 0xffff0000, v186
	v_lshlrev_b32_e32 v186, 16, v187
	v_and_b32_e32 v187, 0xffff0000, v187
	v_and_b32_e32 v221, 0xffff0000, v184
	v_lshlrev_b32_e32 v184, 16, v185
	v_lshlrev_b32_e32 v236, 16, v198
	v_and_b32_e32 v237, 0xffff0000, v198
	v_lshlrev_b32_e32 v198, 16, v199
	v_and_b32_e32 v199, 0xffff0000, v199
	v_lshlrev_b32_e32 v242, 16, v204
	v_and_b32_e32 v243, 0xffff0000, v204
	v_lshlrev_b32_e32 v204, 16, v205
	v_and_b32_e32 v205, 0xffff0000, v205
	v_and_b32_e32 v185, 0xffff0000, v185
	v_lshlrev_b32_e32 v222, 16, v194
	v_and_b32_e32 v223, 0xffff0000, v194
	v_lshlrev_b32_e32 v194, 16, v195
	v_and_b32_e32 v195, 0xffff0000, v195
	v_lshlrev_b32_e32 v224, 16, v200
	v_and_b32_e32 v225, 0xffff0000, v200
	v_lshlrev_b32_e32 v200, 16, v201
	v_lshlrev_b32_e32 v212, 16, v176
	v_and_b32_e32 v213, 0xffff0000, v176
	v_lshlrev_b32_e32 v176, 16, v177
	v_and_b32_e32 v177, 0xffff0000, v177
	v_lshlrev_b32_e32 v214, 16, v178
	v_and_b32_e32 v215, 0xffff0000, v178
	v_lshlrev_b32_e32 v178, 16, v179
	v_and_b32_e32 v179, 0xffff0000, v179
	v_lshlrev_b32_e32 v216, 16, v180
	v_and_b32_e32 v217, 0xffff0000, v180
	v_lshlrev_b32_e32 v180, 16, v181
	v_and_b32_e32 v181, 0xffff0000, v181
	v_lshlrev_b32_e32 v218, 16, v182
	v_and_b32_e32 v219, 0xffff0000, v182
	v_lshlrev_b32_e32 v182, 16, v183
	v_and_b32_e32 v183, 0xffff0000, v183
	v_pk_add_f32 v[112:113], v[112:113], v[212:213]
	v_pk_add_f32 v[114:115], v[114:115], v[176:177]
	v_pk_add_f32 v[120:121], v[120:121], v[214:215]
	v_pk_add_f32 v[122:123], v[122:123], v[178:179]
	v_pk_add_f32 v[130:131], v[130:131], v[180:181]
	v_pk_add_f32 v[138:139], v[138:139], v[182:183]
	v_lshlrev_b32_e32 v176, 16, v208
	v_and_b32_e32 v177, 0xffff0000, v208
	v_lshlrev_b32_e32 v178, 16, v209
	v_and_b32_e32 v179, 0xffff0000, v209
	v_lshlrev_b32_e32 v180, 16, v210
	v_and_b32_e32 v181, 0xffff0000, v210
	v_lshlrev_b32_e32 v182, 16, v211
	v_and_b32_e32 v183, 0xffff0000, v211
	v_and_b32_e32 v201, 0xffff0000, v201
	v_lshlrev_b32_e32 v226, 16, v202
	v_and_b32_e32 v227, 0xffff0000, v202
	v_lshlrev_b32_e32 v232, 16, v192
	v_and_b32_e32 v233, 0xffff0000, v192
	v_lshlrev_b32_e32 v192, 16, v193
	v_and_b32_e32 v193, 0xffff0000, v193
	v_lshlrev_b32_e32 v234, 16, v190
	v_and_b32_e32 v235, 0xffff0000, v190
	v_lshlrev_b32_e32 v190, 16, v191
	v_and_b32_e32 v191, 0xffff0000, v191
	v_pk_add_f32 v[154:155], v[154:155], v[186:187]
	v_pk_add_f32 v[150:151], v[150:151], v[198:199]
	v_pk_add_f32 v[174:175], v[174:175], v[204:205]
	v_lshlrev_b32_e32 v198, 16, v74
	v_and_b32_e32 v199, 0xffff0000, v74
	v_lshlrev_b32_e32 v74, 16, v75
	v_and_b32_e32 v75, 0xffff0000, v75
	v_lshlrev_b32_e32 v204, 16, v72
	v_and_b32_e32 v205, 0xffff0000, v72
	v_lshlrev_b32_e32 v72, 16, v73
	v_and_b32_e32 v73, 0xffff0000, v73
	v_pk_add_f32 v[112:113], v[112:113], v[176:177]
	v_pk_add_f32 v[114:115], v[114:115], v[178:179]
	v_pk_add_f32 v[120:121], v[120:121], v[180:181]
	v_pk_add_f32 v[122:123], v[122:123], v[182:183]
	v_lshlrev_b32_e32 v202, 16, v203
	v_and_b32_e32 v203, 0xffff0000, v203
	v_lshlrev_b32_e32 v238, 16, v196
	v_and_b32_e32 v239, 0xffff0000, v196
	v_lshlrev_b32_e32 v196, 16, v197
	v_and_b32_e32 v197, 0xffff0000, v197
	v_lshlrev_b32_e32 v240, 16, v206
	v_and_b32_e32 v241, 0xffff0000, v206
	v_lshlrev_b32_e32 v206, 16, v207
	v_and_b32_e32 v207, 0xffff0000, v207
	v_pk_add_f32 v[128:129], v[128:129], v[216:217]
	v_pk_add_f32 v[118:119], v[118:119], v[184:185]
	v_pk_add_f32 v[126:127], v[126:127], v[194:195]
	v_pk_add_f32 v[134:135], v[134:135], v[200:201]
	v_pk_add_f32 v[140:141], v[140:141], v[226:227]
	v_pk_add_f32 v[152:153], v[152:153], v[230:231]
	v_pk_add_f32 v[162:163], v[162:163], v[192:193]
	v_pk_add_f32 v[170:171], v[170:171], v[190:191]
	v_pk_add_f32 v[148:149], v[148:149], v[236:237]
	v_lshlrev_b32_e32 v184, 16, v90
	v_and_b32_e32 v185, 0xffff0000, v90
	v_lshlrev_b32_e32 v90, 16, v91
	v_and_b32_e32 v91, 0xffff0000, v91
	v_lshlrev_b32_e32 v190, 16, v84
	v_and_b32_e32 v191, 0xffff0000, v84
	v_lshlrev_b32_e32 v84, 16, v85
	v_and_b32_e32 v85, 0xffff0000, v85
	v_lshlrev_b32_e32 v192, 16, v82
	v_and_b32_e32 v193, 0xffff0000, v82
	v_lshlrev_b32_e32 v82, 16, v83
	v_and_b32_e32 v83, 0xffff0000, v83
	v_lshlrev_b32_e32 v194, 16, v80
	v_and_b32_e32 v195, 0xffff0000, v80
	v_pk_add_f32 v[74:75], v[154:155], v[74:75]
	v_pk_add_f32 v[72:73], v[150:151], v[72:73]
	v_mov_b32_e32 v150, v113
	v_mov_b32_e32 v151, v115
	v_mov_b32_e32 v154, v121
	v_mov_b32_e32 v155, v123
	v_lshlrev_b32_e32 v228, 16, v188
	v_and_b32_e32 v229, 0xffff0000, v188
	v_lshlrev_b32_e32 v188, 16, v189
	v_and_b32_e32 v189, 0xffff0000, v189
	v_pk_add_f32 v[136:137], v[136:137], v[218:219]
	v_pk_add_f32 v[142:143], v[142:143], v[202:203]
	v_pk_add_f32 v[156:157], v[156:157], v[238:239]
	v_pk_add_f32 v[158:159], v[158:159], v[196:197]
	v_pk_add_f32 v[166:167], v[166:167], v[206:207]
	v_lshlrev_b32_e32 v186, 16, v88
	v_and_b32_e32 v187, 0xffff0000, v88
	v_lshlrev_b32_e32 v88, 16, v89
	v_and_b32_e32 v89, 0xffff0000, v89
	v_lshlrev_b32_e32 v80, 16, v81
	v_and_b32_e32 v81, 0xffff0000, v81
	v_lshlrev_b32_e32 v206, 16, v66
	v_and_b32_e32 v207, 0xffff0000, v66
	v_lshlrev_b32_e32 v66, 16, v67
	v_and_b32_e32 v67, 0xffff0000, v67
	v_pk_add_f32 v[128:129], v[128:129], v[184:185]
	v_pk_add_f32 v[90:91], v[130:131], v[90:91]
	v_pk_add_f32 v[84:85], v[126:127], v[84:85]
	v_pk_add_f32 v[82:83], v[134:135], v[82:83]
	v_pk_add_f32 v[126:127], v[140:141], v[194:195]
	v_pk_add_f32 v[134:135], v[152:153], v[198:199]
	v_pk_add_f32 v[140:141], v[148:149], v[204:205]
	v_mov_b32_e32 v148, v112
	v_mov_b32_e32 v149, v114
	v_mov_b32_e32 v152, v120
	v_mov_b32_e32 v153, v122
	v_pk_mul_f32 v[150:151], v[150:151], v[150:151]
	v_pk_mul_f32 v[154:155], v[154:155], v[154:155]
	v_pk_add_f32 v[116:117], v[116:117], v[220:221]
	v_pk_add_f32 v[146:147], v[146:147], v[188:189]
	v_pk_add_f32 v[160:161], v[160:161], v[232:233]
	v_lshlrev_b32_e32 v188, 16, v86
	v_and_b32_e32 v189, 0xffff0000, v86
	v_lshlrev_b32_e32 v86, 16, v87
	v_and_b32_e32 v87, 0xffff0000, v87
	v_lshlrev_b32_e32 v200, 16, v76
	v_and_b32_e32 v201, 0xffff0000, v76
	v_lshlrev_b32_e32 v76, 16, v77
	v_and_b32_e32 v77, 0xffff0000, v77
	v_pk_add_f32 v[130:131], v[136:137], v[186:187]
	v_pk_add_f32 v[88:89], v[138:139], v[88:89]
	v_pk_add_f32 v[80:81], v[142:143], v[80:81]
	v_pk_add_f32 v[142:143], v[156:157], v[206:207]
	v_pk_add_f32 v[66:67], v[158:159], v[66:67]
	v_mul_f32_e32 v156, v129, v129
	v_mul_f32_e32 v158, v91, v91
	v_pk_fma_f32 v[148:149], v[148:149], v[148:149], v[150:151]
	v_pk_fma_f32 v[150:151], v[152:153], v[152:153], v[154:155]
	v_lshlrev_b32_e32 v208, 16, v68
	v_and_b32_e32 v209, 0xffff0000, v68
	v_lshlrev_b32_e32 v68, 16, v69
	v_and_b32_e32 v69, 0xffff0000, v69
	v_pk_add_f32 v[116:117], v[116:117], v[188:189]
	v_pk_add_f32 v[86:87], v[118:119], v[86:87]
	v_pk_add_f32 v[136:137], v[160:161], v[200:201]
	v_pk_add_f32 v[76:77], v[162:163], v[76:77]
	v_pk_mul_f32 v[160:161], v[130:131], v[130:131]
	v_pk_mul_f32 v[162:163], v[88:89], v[88:89]
	v_pk_fma_f32 v[156:157], v[128:129], v[128:129], v[156:157] op_sel_hi:[1,1,0]
	v_pk_fma_f32 v[158:159], v[90:91], v[90:91], v[158:159] op_sel_hi:[1,1,0]
	v_pk_add_f32 v[148:149], v[148:149], v[148:149] op_sel:[0,1] op_sel_hi:[1,0]
	v_pk_add_f32 v[150:151], v[150:151], v[150:151] op_sel:[0,1] op_sel_hi:[1,0]
	v_pk_add_f32 v[124:125], v[124:125], v[222:223]
	v_pk_add_f32 v[132:133], v[132:133], v[224:225]
	v_pk_add_f32 v[144:145], v[144:145], v[228:229]
	v_pk_add_f32 v[164:165], v[164:165], v[240:241]
	v_lshlrev_b32_e32 v196, 16, v78
	v_and_b32_e32 v197, 0xffff0000, v78
	v_pk_add_f32 v[68:69], v[166:167], v[68:69]
	v_mov_b32_e32 v166, v117
	v_mov_b32_e32 v167, v87
	v_mov_b32_e32 v157, v162
	v_mov_b32_e32 v159, v163
	v_mov_b32_e32 v149, v160
	v_mov_b32_e32 v151, v161
	v_pk_add_f32 v[168:169], v[168:169], v[234:235]
	v_lshlrev_b32_e32 v202, 16, v70
	v_and_b32_e32 v203, 0xffff0000, v70
	v_lshlrev_b32_e32 v70, 16, v71
	v_and_b32_e32 v71, 0xffff0000, v71
	v_pk_add_f32 v[118:119], v[124:125], v[190:191]
	v_pk_add_f32 v[124:125], v[132:133], v[192:193]
	v_pk_add_f32 v[132:133], v[144:145], v[196:197]
	v_pk_add_f32 v[144:145], v[164:165], v[208:209]
	v_mov_b32_e32 v164, v116
	v_mov_b32_e32 v165, v86
	v_pk_mul_f32 v[166:167], v[166:167], v[166:167]
	v_pk_add_f32 v[156:157], v[156:157], v[158:159]
	v_pk_add_f32 v[148:149], v[148:149], v[150:151]
	v_pk_add_f32 v[172:173], v[172:173], v[242:243]
	v_lshlrev_b32_e32 v78, 16, v79
	v_and_b32_e32 v79, 0xffff0000, v79
	v_lshlrev_b32_e32 v210, 16, v64
	v_and_b32_e32 v211, 0xffff0000, v64
	v_lshlrev_b32_e32 v64, 16, v65
	v_and_b32_e32 v65, 0xffff0000, v65
	v_pk_add_f32 v[138:139], v[168:169], v[202:203]
	v_pk_add_f32 v[70:71], v[170:171], v[70:71]
	v_mul_f32_e32 v168, v119, v119
	v_mul_f32_e32 v170, v85, v85
	v_pk_fma_f32 v[152:153], v[164:165], v[164:165], v[166:167]
	v_pk_add_f32 v[148:149], v[148:149], v[156:157]
	v_pk_add_f32 v[78:79], v[146:147], v[78:79]
	v_pk_add_f32 v[146:147], v[172:173], v[210:211]
	v_pk_add_f32 v[64:65], v[174:175], v[64:65]
	v_pk_mul_f32 v[172:173], v[124:125], v[124:125]
	v_pk_mul_f32 v[174:175], v[82:83], v[82:83]
	v_pk_fma_f32 v[168:169], v[118:119], v[118:119], v[168:169] op_sel_hi:[1,1,0]
	v_pk_fma_f32 v[170:171], v[84:85], v[84:85], v[170:171] op_sel_hi:[1,1,0]
	v_pk_add_f32 v[152:153], v[152:153], v[152:153] op_sel:[0,1] op_sel_hi:[1,0]
	v_pk_add_f32 v[148:149], v[148:149], v[148:149] op_sel:[0,1] op_sel_hi:[1,0]
	v_mov_b32_e32 v178, v127
	v_mov_b32_e32 v179, v81
	v_mov_b32_e32 v169, v174
	v_mov_b32_e32 v171, v175
	v_mov_b32_e32 v153, v173
	v_mov_b32_e32 v149, v172
	v_mov_b32_e32 v176, v126
	v_mov_b32_e32 v177, v80
	v_pk_mul_f32 v[178:179], v[178:179], v[178:179]
	v_pk_add_f32 v[158:159], v[168:169], v[170:171]
	v_pk_add_f32 v[148:149], v[148:149], v[152:153]
	v_mul_f32_e32 v180, v133, v133
	v_mul_f32_e32 v182, v79, v79
	v_pk_fma_f32 v[154:155], v[176:177], v[176:177], v[178:179]
	v_pk_add_f32 v[148:149], v[148:149], v[158:159]
	v_pk_mul_f32 v[184:185], v[134:135], v[134:135]
	v_pk_mul_f32 v[186:187], v[74:75], v[74:75]
	v_pk_fma_f32 v[180:181], v[132:133], v[132:133], v[180:181] op_sel_hi:[1,1,0]
	v_pk_fma_f32 v[182:183], v[78:79], v[78:79], v[182:183] op_sel_hi:[1,1,0]
	v_pk_add_f32 v[154:155], v[154:155], v[154:155] op_sel:[0,1] op_sel_hi:[1,0]
	v_pk_add_f32 v[148:149], v[148:149], v[148:149] op_sel:[0,1] op_sel_hi:[1,0]
	v_mov_b32_e32 v190, v137
	v_mov_b32_e32 v191, v77
	v_mov_b32_e32 v181, v186
	v_mov_b32_e32 v183, v187
	v_mov_b32_e32 v155, v185
	v_mov_b32_e32 v149, v184
	v_mov_b32_e32 v188, v136
	v_mov_b32_e32 v189, v76
	v_pk_mul_f32 v[190:191], v[190:191], v[190:191]
	v_pk_add_f32 v[166:167], v[180:181], v[182:183]
	v_pk_add_f32 v[148:149], v[148:149], v[154:155]
	v_mul_f32_e32 v192, v139, v139
	v_mul_f32_e32 v194, v71, v71
	v_pk_fma_f32 v[162:163], v[188:189], v[188:189], v[190:191]
	v_pk_add_f32 v[148:149], v[148:149], v[166:167]
	v_pk_mul_f32 v[196:197], v[140:141], v[140:141]
	v_pk_mul_f32 v[198:199], v[72:73], v[72:73]
	v_pk_fma_f32 v[192:193], v[138:139], v[138:139], v[192:193] op_sel_hi:[1,1,0]
	v_pk_fma_f32 v[194:195], v[70:71], v[70:71], v[194:195] op_sel_hi:[1,1,0]
	v_pk_add_f32 v[162:163], v[162:163], v[162:163] op_sel:[0,1] op_sel_hi:[1,0]
	v_pk_add_f32 v[148:149], v[148:149], v[148:149] op_sel:[0,1] op_sel_hi:[1,0]
	v_mov_b32_e32 v202, v143
	v_mov_b32_e32 v203, v67
	v_mov_b32_e32 v193, v198
	v_mov_b32_e32 v195, v199
	v_mov_b32_e32 v163, v197
	v_mov_b32_e32 v149, v196
	v_mov_b32_e32 v200, v142
	v_mov_b32_e32 v201, v66
	v_pk_mul_f32 v[202:203], v[202:203], v[202:203]
	v_pk_add_f32 v[168:169], v[192:193], v[194:195]
	v_pk_add_f32 v[148:149], v[148:149], v[162:163]
	v_mul_f32_e32 v204, v145, v145
	v_mul_f32_e32 v206, v69, v69
	v_pk_fma_f32 v[164:165], v[200:201], v[200:201], v[202:203]
	v_pk_add_f32 v[148:149], v[148:149], v[168:169]
	v_pk_mul_f32 v[208:209], v[146:147], v[146:147]
	v_pk_mul_f32 v[210:211], v[64:65], v[64:65]
	v_pk_fma_f32 v[204:205], v[144:145], v[144:145], v[204:205] op_sel_hi:[1,1,0]
	v_pk_fma_f32 v[206:207], v[68:69], v[68:69], v[206:207] op_sel_hi:[1,1,0]
	v_pk_add_f32 v[164:165], v[164:165], v[164:165] op_sel:[0,1] op_sel_hi:[1,0]
	v_pk_add_f32 v[148:149], v[148:149], v[148:149] op_sel:[0,1] op_sel_hi:[1,0]
	v_mov_b32_e32 v205, v210
	v_mov_b32_e32 v207, v211
	v_mov_b32_e32 v165, v209
	v_mov_b32_e32 v149, v208
	v_pk_add_f32 v[170:171], v[204:205], v[206:207]
	v_pk_add_f32 v[148:149], v[148:149], v[164:165]
	s_nop 0
	v_pk_add_f32 v[148:149], v[148:149], v[170:171]
	s_nop 0
	v_add_f32_e32 v148, v148, v149
	ds_bpermute_b32 v149, v104, v148
	s_waitcnt lgkmcnt(0)
	v_add_f32_e32 v148, v148, v149
	ds_bpermute_b32 v149, v105, v148
	s_waitcnt lgkmcnt(0)
	v_add_f32_e32 v148, v148, v149
	ds_bpermute_b32 v149, v106, v148
	s_waitcnt lgkmcnt(0)
	v_add_f32_e32 v148, v148, v149
	ds_bpermute_b32 v149, v107, v148
	s_waitcnt lgkmcnt(0)
	v_add_f32_e32 v148, v148, v149
	ds_bpermute_b32 v149, v108, v148
	s_waitcnt lgkmcnt(0)
	v_add_f32_e32 v148, v148, v149
	ds_bpermute_b32 v149, v109, v148
	s_waitcnt lgkmcnt(0)
	v_add_f32_e32 v148, v148, v149
	v_fmamk_f32 v148, v148, 0x39800000, v110
	v_mul_f32_e32 v149, 0x4f800000, v148
	v_cmp_gt_f32_e32 vcc, s28, v148
	s_nop 1
	v_cndmask_b32_e32 v148, v148, v149, vcc
	v_sqrt_f32_e32 v149, v148
	s_nop 0
	v_add_u32_e32 v150, -1, v149
	v_add_u32_e32 v151, 1, v149
	v_fma_f32 v152, -v150, v149, v148
	v_fma_f32 v153, -v151, v149, v148
	v_cmp_ge_f32_e64 s[0:1], 0, v152
	s_nop 1
	v_cndmask_b32_e64 v149, v149, v150, s[0:1]
	v_cmp_lt_f32_e64 s[0:1], 0, v153
	s_nop 1
	v_cndmask_b32_e64 v149, v149, v151, s[0:1]
	v_mul_f32_e32 v150, 0x37800000, v149
	v_cndmask_b32_e32 v149, v149, v150, vcc
	v_cmp_class_f32_e32 vcc, v148, v111
	s_nop 1
	v_cndmask_b32_e32 v148, v149, v148, vcc
	v_div_scale_f32 v149, s[0:1], v148, v148, 1.0
	v_rcp_f32_e32 v151, v149
	v_div_scale_f32 v150, vcc, 1.0, v148, 1.0
	v_fma_f32 v152, -v149, v151, 1.0
	v_fmac_f32_e32 v151, v152, v151
	v_mul_f32_e32 v152, v150, v151
	v_fma_f32 v153, -v149, v152, v150
	v_fmac_f32_e32 v152, v153, v151
	v_fma_f32 v149, -v149, v152, v150
	v_div_fmas_f32 v149, v149, v151, v152
	v_div_fixup_f32 v148, v149, v148, 1.0
	v_pk_mul_f32 v[112:113], v[112:113], v[148:149] op_sel_hi:[1,0]
	v_pk_mul_f32 v[114:115], v[114:115], v[148:149] op_sel_hi:[1,0]
	v_pk_mul_f32 v[120:121], v[120:121], v[148:149] op_sel_hi:[1,0]
	v_pk_mul_f32 v[122:123], v[122:123], v[148:149] op_sel_hi:[1,0]
	v_pk_mul_f32 v[128:129], v[128:129], v[148:149] op_sel_hi:[1,0]
	v_pk_mul_f32 v[90:91], v[90:91], v[148:149] op_sel_hi:[1,0]
	v_pk_mul_f32 v[130:131], v[130:131], v[148:149] op_sel_hi:[1,0]
	v_pk_mul_f32 v[88:89], v[88:89], v[148:149] op_sel_hi:[1,0]
	v_pk_mul_f32 v[116:117], v[116:117], v[148:149] op_sel_hi:[1,0]
	v_pk_mul_f32 v[86:87], v[86:87], v[148:149] op_sel_hi:[1,0]
	v_pk_mul_f32 v[118:119], v[118:119], v[148:149] op_sel_hi:[1,0]
	v_pk_mul_f32 v[84:85], v[84:85], v[148:149] op_sel_hi:[1,0]
	v_pk_mul_f32 v[124:125], v[124:125], v[148:149] op_sel_hi:[1,0]
	v_pk_mul_f32 v[82:83], v[82:83], v[148:149] op_sel_hi:[1,0]
	v_pk_mul_f32 v[126:127], v[126:127], v[148:149] op_sel_hi:[1,0]
	v_pk_mul_f32 v[80:81], v[80:81], v[148:149] op_sel_hi:[1,0]
	v_pk_mul_f32 v[132:133], v[132:133], v[148:149] op_sel_hi:[1,0]
	v_pk_mul_f32 v[78:79], v[78:79], v[148:149] op_sel_hi:[1,0]
	v_pk_mul_f32 v[134:135], v[134:135], v[148:149] op_sel_hi:[1,0]
	v_pk_mul_f32 v[74:75], v[74:75], v[148:149] op_sel_hi:[1,0]
	v_pk_mul_f32 v[136:137], v[136:137], v[148:149] op_sel_hi:[1,0]
	v_pk_mul_f32 v[76:77], v[76:77], v[148:149] op_sel_hi:[1,0]
	v_pk_mul_f32 v[138:139], v[138:139], v[148:149] op_sel_hi:[1,0]
	v_pk_mul_f32 v[70:71], v[70:71], v[148:149] op_sel_hi:[1,0]
	v_pk_mul_f32 v[140:141], v[140:141], v[148:149] op_sel_hi:[1,0]
	v_pk_mul_f32 v[72:73], v[72:73], v[148:149] op_sel_hi:[1,0]
	v_pk_mul_f32 v[142:143], v[142:143], v[148:149] op_sel_hi:[1,0]
	v_pk_mul_f32 v[66:67], v[66:67], v[148:149] op_sel_hi:[1,0]
	v_pk_mul_f32 v[144:145], v[144:145], v[148:149] op_sel_hi:[1,0]
	v_pk_mul_f32 v[68:69], v[68:69], v[148:149] op_sel_hi:[1,0]
	v_pk_mul_f32 v[146:147], v[146:147], v[148:149] op_sel_hi:[1,0]
	v_pk_mul_f32 v[64:65], v[64:65], v[148:149] op_sel_hi:[1,0]
	v_pk_mul_f32 v[2:3], v[114:115], v[2:3]
	v_pk_mul_f32 v[0:1], v[112:113], v[0:1]
	v_pk_mul_f32 v[10:11], v[122:123], v[10:11]
	v_pk_mul_f32 v[8:9], v[120:121], v[8:9]
	v_pk_mul_f32 v[18:19], v[90:91], v[18:19]
	v_pk_mul_f32 v[16:17], v[128:129], v[16:17]
	v_pk_mul_f32 v[26:27], v[88:89], v[26:27]
	v_pk_mul_f32 v[24:25], v[130:131], v[24:25]
	v_pk_mul_f32 v[6:7], v[86:87], v[6:7]
	v_pk_mul_f32 v[4:5], v[116:117], v[4:5]
	v_pk_mul_f32 v[14:15], v[84:85], v[14:15]
	v_pk_mul_f32 v[12:13], v[118:119], v[12:13]
	v_pk_mul_f32 v[22:23], v[82:83], v[22:23]
	v_pk_mul_f32 v[20:21], v[124:125], v[20:21]
	v_pk_mul_f32 v[30:31], v[80:81], v[30:31]
	v_pk_mul_f32 v[28:29], v[126:127], v[28:29]
	v_pk_mul_f32 v[34:35], v[78:79], v[34:35]
	v_pk_mul_f32 v[32:33], v[132:133], v[32:33]
	v_pk_mul_f32 v[42:43], v[74:75], v[42:43]
	v_pk_mul_f32 v[40:41], v[134:135], v[40:41]
	v_pk_mul_f32 v[50:51], v[76:77], v[50:51]
	v_pk_mul_f32 v[48:49], v[136:137], v[48:49]
	v_pk_mul_f32 v[58:59], v[70:71], v[58:59]
	v_pk_mul_f32 v[56:57], v[138:139], v[56:57]
	v_pk_mul_f32 v[38:39], v[72:73], v[38:39]
	v_pk_mul_f32 v[36:37], v[140:141], v[36:37]
	v_pk_mul_f32 v[46:47], v[66:67], v[46:47]
	v_pk_mul_f32 v[44:45], v[142:143], v[44:45]
	v_pk_mul_f32 v[54:55], v[68:69], v[54:55]
	v_pk_mul_f32 v[52:53], v[144:145], v[52:53]
	v_pk_mul_f32 v[62:63], v[64:65], v[62:63]
	v_pk_mul_f32 v[60:61], v[146:147], v[60:61]
	buffer_store_dwordx4 v[0:3], v92, s[4:7], 0 offen nt
	buffer_store_dwordx4 v[8:11], v94, s[4:7], 0 offen nt
	buffer_store_dwordx4 v[16:19], v95, s[4:7], 0 offen nt
	buffer_store_dwordx4 v[24:27], v96, s[4:7], 0 offen nt
	buffer_store_dwordx4 v[4:7], v92, s[4:7], s19 offen nt
	buffer_store_dwordx4 v[12:15], v94, s[4:7], s19 offen nt
	buffer_store_dwordx4 v[20:23], v95, s[4:7], s19 offen nt
	buffer_store_dwordx4 v[28:31], v96, s[4:7], s19 offen nt
	buffer_store_dwordx4 v[32:35], v92, s[4:7], s2 offen nt
	buffer_store_dwordx4 v[40:43], v94, s[4:7], s2 offen nt
	buffer_store_dwordx4 v[48:51], v95, s[4:7], s2 offen nt
	buffer_store_dwordx4 v[56:59], v96, s[4:7], s2 offen nt
	buffer_store_dwordx4 v[36:39], v92, s[4:7], s27 offen nt
	buffer_store_dwordx4 v[44:47], v94, s[4:7], s27 offen nt
	buffer_store_dwordx4 v[52:55], v95, s[4:7], s27 offen nt
	buffer_store_dwordx4 v[60:63], v96, s[4:7], s27 offen nt
	s_cbranch_scc1 .LBB0_1001
